# P1 load balance: lower half of the grid (7 main units) takes 1 pp0 unit, upper half (6 main units) takes 3 instead of 4
# baseline (speedup 1.0000x reference)
.LBB0_175:
	s_add_u32 s74, s88, 0x8800000
	s_addc_u32 s75, s89, 0
	s_cmpk_eq_i32 s2, 0x100
	s_cselect_b64 s[0:1], -1, 0
	s_cmpk_lt_i32 s3, 0x80
	s_cselect_b64 s[4:5], -1, 0
	v_writelane_b32 v254, s94, 44
	s_and_b64 s[0:1], s[0:1], s[4:5]
	s_and_b64 vcc, exec, s[0:1]
	v_writelane_b32 v254, s95, 45
	v_writelane_b32 v254, s96, 46
	s_nop 1
	v_writelane_b32 v254, s97, 47
	s_nop 0
	s_add_i32 s6, s3, 0xffffff80
	s_cmpk_eq_i32 s2, 0x100
	s_cselect_b64 s[0:1], -1, 0
	s_and_b64 s[4:5], s[0:1], exec
	v_readlane_b32 s4, v254, 3
	s_nop 0
	v_mbcnt_lo_u32_b32 v0, -1, 0
	v_mbcnt_hi_u32_b32 v0, -1, v0
	s_cmpk_gt_i32 s3, 0x1ff
	v_or_b32_e32 v8, s4, v0
	s_nop 0
	v_readfirstlane_b32 s8, v8
	s_cbranch_scc1 .LBB0_200
	s_ashr_i32 s26, s3, 31
	s_lshr_b32 s4, s26, 29
	s_add_i32 s7, s3, s4
	s_and_b32 s4, s7, -8
	s_sub_i32 s6, s3, s4
	s_cmp_gt_i32 s6, -1
	s_cbranch_scc0 .LBB0_179
	s_lshl_b32 s9, s6, 6
	s_ashr_i32 s4, s7, 3
	s_cbranch_execz .LBB0_180
	s_branch .LBB0_181

.LBB0_183:
	s_lshl_b32 s6, s6, 5
	s_and_b32 s96, s6, 0x60
	s_lshl_b32 s95, s7, 6
	s_lshl_b32 s10, s7, 13
	s_lshl_b32 s11, s96, 7
	s_and_b64 s[0:1], s[0:1], exec
	s_mov_b64 s[6:7], 0x80
	s_cselect_b32 s2, 0x80, s2
	s_add_i32 m0, s30, 0x18000
	v_lshl_add_u64 v[6:7], v[6:7], 0, s[6:7]
	s_waitcnt vmcnt(2)
	s_barrier
	global_load_lds_dwordx4 v[6:7], off
	v_lshl_add_u64 v[4:5], v[4:5], 0, s[6:7]
	s_add_i32 m0, s30, 0x1a000
	s_add_i32 s97, s30, 0x8000
	s_add_i32 s33, s30, 0xa000
	global_load_lds_dwordx4 v[4:5], off
	v_lshl_add_u64 v[0:1], v[0:1], 0, s[6:7]
	s_mov_b32 m0, s97
	s_add_u32 s0, s64, 0x10080
	global_load_lds_dwordx4 v[0:1], off
	v_lshl_add_u64 v[0:1], v[2:3], 0, s[6:7]
	s_mov_b32 m0, s33
	s_addc_u32 s1, s65, 0
	global_load_lds_dwordx4 v[0:1], off
	s_add_i32 m0, s30, 0x1c000
	v_lshl_add_u64 v[0:1], s[0:1], 0, v[130:131]
	global_load_lds_dwordx4 v[0:1], off
	v_lshl_add_u64 v[0:1], s[0:1], 0, v[134:135]
	s_add_i32 m0, s30, 0x1e000
	s_movk_i32 s0, 0x3c0
	global_load_lds_dwordx4 v[0:1], off
	v_and_b32_e32 v0, 48, v8
	v_lshlrev_b32_e32 v1, 6, v8
	v_and_or_b32 v0, v1, s0, v0
	v_lshlrev_b32_e32 v1, 2, v8
	v_and_b32_e32 v1, 32, v1
	s_waitcnt vmcnt(6)
	s_cmpk_lt_u32 s8, 0x100
	s_sext_i32_i8 s9, s12
	v_bitop3_b32 v2, v0, s10, v1 bitop3:0xde
	v_bitop3_b32 v142, s11, v0, v1 bitop3:0xf6
	s_cselect_b64 s[12:13], -1, 0
	s_cmpk_lt_i32 s3, 0x80
	s_cselect_b32 s2, 0x200, s2
	s_add_i32 s41, 0, 0x10000
	s_add_i32 s8, 0, 0x14000
	s_ashr_i32 s40, s2, 31
	v_mov_b64_e32 v[136:137], 0x200
	v_mov_b64_e32 v[138:139], 0x1ff
	v_add_u32_e32 v143, s41, v142
	v_add_u32_e32 v144, s8, v142
	v_add_u32_e32 v145, 0, v2
	s_barrier
	s_branch .LBB0_186
